# attention work queue: 8 consecutive q-blocks of the same (b,h) adjacent so concurrent items share K/V tiles in L2/MALL
# speedup vs baseline: 1.0271x; 1.0271x over previous
; DI void phase2(const Params& p, char* smem, const int g_wave) {
;     ...
;       int qb, bh;
;       if (prm) { int a = it - N0; qb = 31 - (a >> 6); bh = a & 63; } else { qb = 0; bh = it - N2; }
;       const int b = bh >> 3, h = bh & 7;
;       const size_t rowq = prm ? (size_t)b * 8192 + qb * 256 : (size_t)TP + b * 64;
.LBB0_692:
	s_add_i32 s4, s6, 0xffffff80
	s_lshr_b32 s5, s4, 9
	s_lshl_b32 s5, s5, 3
	s_and_b32 s50, s4, 7
	s_add_i32 s5, s5, s50
	s_sub_i32 s78, 31, s5
	s_bfe_u32 s50, s4, 0x60003
